# compression MLP second matmul: 32 weight loads and 4 fragment reads issued together (one round trip instead of four)
# speedup vs baseline: 1.0017x; 1.0017x over previous
.LBB0_550:
	v_ashrrev_i32_e32 v59, 1, v58
	v_add_u32_e32 v59, v59, v53
	v_lshl_add_u64 v[60:61], v[54:55], 0, s[8:9]
	s_mov_b32 s13, 0x4b80000
	v_min_i32_e32 v59, 0x1fff, v59
	v_add_co_u32_e32 v90, vcc, s13, v60
	v_add_u32_e32 v59, s3, v59
	s_nop 0
	v_addc_co_u32_e32 v91, vcc, 0, v61, vcc
	v_mad_i64_i32 v[106:107], s[30:31], v59, s23, v[56:57]
	s_mov_b32 s13, 0x4b90000
	v_add_co_u32_e64 v94, s[44:45], s13, v60
	s_mov_b32 s13, 0x4ba0000
	s_nop 0
	v_addc_co_u32_e64 v95, vcc, 0, v61, s[44:45]
	v_add_co_u32_e64 v96, s[46:47], s13, v60
	s_mov_b32 s13, 0x4bb0000
	s_nop 0
	v_addc_co_u32_e64 v97, vcc, 0, v61, s[46:47]
	v_add_co_u32_e64 v98, s[48:49], s13, v60
	s_mov_b32 s13, 0x4bc0000
	s_nop 0
	v_addc_co_u32_e64 v99, vcc, 0, v61, s[48:49]
	v_add_co_u32_e64 v100, s[50:51], s13, v60
	s_mov_b32 s13, 0x4bd0000
	s_nop 0
	v_addc_co_u32_e64 v101, vcc, 0, v61, s[50:51]
	v_add_co_u32_e64 v102, s[52:53], s13, v60
	s_mov_b32 s13, 0x4be0000
	s_nop 0
	v_addc_co_u32_e64 v103, vcc, 0, v61, s[52:53]
	v_add_co_u32_e64 v104, s[54:55], s13, v60
	s_mov_b32 s13, 0x4bf0000
	s_nop 0
	v_addc_co_u32_e64 v105, vcc, 0, v61, s[54:55]
	v_add_co_u32_e64 v60, s[56:57], s13, v60
	s_add_u32 s8, s8, 0x80
	s_nop 0
	v_addc_co_u32_e64 v61, vcc, 0, v61, s[56:57]
	s_addc_u32 s9, s9, 0
	s_cmpk_eq_i32 s8, 0x200
	v_add_u32_e32 v58, 2, v58
	global_load_dwordx4 v[86:89], v[106:107], off
	global_load_dwordx4 v[82:85], v[106:107], off offset:64
	global_load_dwordx4 v[212:215], v[90:91], off
	global_load_dwordx4 v[216:219], v[94:95], off
	global_load_dwordx4 v[220:223], v[96:97], off
	global_load_dwordx4 v[224:227], v[98:99], off
	global_load_dwordx4 v[228:231], v[100:101], off
	global_load_dwordx4 v[232:235], v[102:103], off
	global_load_dwordx4 v[236:239], v[104:105], off
	global_load_dwordx4 v[240:243], v[60:61], off
	global_load_dwordx4 v[244:247], v[90:91], off offset:64
	global_load_dwordx4 v[248:251], v[94:95], off offset:64
	global_load_dwordx4 v[138:141], v[96:97], off offset:64
	global_load_dwordx4 v[142:145], v[98:99], off offset:64
	global_load_dwordx4 v[146:149], v[100:101], off offset:64
	global_load_dwordx4 v[150:153], v[102:103], off offset:64
	global_load_dwordx4 v[176:179], v[104:105], off offset:64
	global_load_dwordx4 v[180:183], v[60:61], off offset:64
	s_waitcnt vmcnt(8)
	v_mfma_f32_16x16x32_bf16 v[2:5], v[86:89], v[212:215], v[2:5]
	v_mfma_f32_16x16x32_bf16 v[6:9], v[86:89], v[216:219], v[6:9]
	v_mfma_f32_16x16x32_bf16 v[10:13], v[86:89], v[220:223], v[10:13]
	v_mfma_f32_16x16x32_bf16 v[14:17], v[86:89], v[224:227], v[14:17]
	v_mfma_f32_16x16x32_bf16 v[18:21], v[86:89], v[228:231], v[18:21]
	v_mfma_f32_16x16x32_bf16 v[22:25], v[86:89], v[232:235], v[22:25]
	v_mfma_f32_16x16x32_bf16 v[26:29], v[86:89], v[236:239], v[26:29]
	v_mfma_f32_16x16x32_bf16 v[30:33], v[86:89], v[240:243], v[30:33]
	s_waitcnt vmcnt(0)
	v_mfma_f32_16x16x32_bf16 v[2:5], v[82:85], v[244:247], v[2:5]
	v_mfma_f32_16x16x32_bf16 v[6:9], v[82:85], v[248:251], v[6:9]
	v_mfma_f32_16x16x32_bf16 v[10:13], v[82:85], v[138:141], v[10:13]
	v_mfma_f32_16x16x32_bf16 v[14:17], v[82:85], v[142:145], v[14:17]
	v_mfma_f32_16x16x32_bf16 v[18:21], v[82:85], v[146:149], v[18:21]
	v_mfma_f32_16x16x32_bf16 v[22:25], v[82:85], v[150:153], v[22:25]
	v_mfma_f32_16x16x32_bf16 v[26:29], v[82:85], v[176:179], v[26:29]
	v_mfma_f32_16x16x32_bf16 v[30:33], v[82:85], v[180:183], v[30:33]
	s_cbranch_scc0 .LBB0_550
	v_add_u32_e32 v53, 0x4000, v79
	ds_write2_b32 v53, v2, v6 offset1:16
	ds_write2_b32 v53, v3, v7 offset0:132 offset1:148
	v_add_u32_e32 v2, 0x4400, v79
	ds_write2_b32 v2, v4, v8 offset0:8 offset1:24
	ds_write2_b32 v2, v5, v9 offset0:140 offset1:156
	ds_write2_b32 v53, v10, v14 offset0:32 offset1:48
	ds_write2_b32 v53, v11, v15 offset0:164 offset1:180
	ds_write2_b32 v2, v12, v16 offset0:40 offset1:56
	ds_write2_b32 v2, v13, v17 offset0:172 offset1:188
	ds_write2_b32 v53, v18, v22 offset0:64 offset1:80
	ds_write2_b32 v53, v19, v23 offset0:196 offset1:212
	ds_write2_b32 v2, v20, v24 offset0:72 offset1:88
	ds_write2_b32 v2, v21, v25 offset0:204 offset1:220
	ds_write2_b32 v53, v26, v30 offset0:96 offset1:112
	ds_write2_b32 v53, v27, v31 offset0:228 offset1:244
	ds_write2_b32 v2, v28, v32 offset0:104 offset1:120
	ds_write2_b32 v2, v29, v33 offset0:236 offset1:252
	s_waitcnt lgkmcnt(0)
	s_barrier
	ds_read_b128 v[2:5], v74 offset:16384
	s_movk_i32 s8, 0x7fff
	s_waitcnt lgkmcnt(0)
	v_pk_add_f32 v[6:7], v[4:5], 0 op_sel_hi:[1,0]
	v_pk_add_f32 v[8:9], v[2:3], 0 op_sel_hi:[1,0]
	ds_read_b128 v[2:5], v74 offset:24832
	s_waitcnt lgkmcnt(0)
	v_pk_add_f32 v[6:7], v[6:7], v[4:5]
	v_pk_add_f32 v[8:9], v[8:9], v[2:3]
	ds_read_b128 v[2:5], v74 offset:33280
	s_waitcnt lgkmcnt(0)
	v_pk_add_f32 v[6:7], v[6:7], v[4:5]
	v_pk_add_f32 v[8:9], v[8:9], v[2:3]
	ds_read_b128 v[2:5], v74 offset:41728
	s_waitcnt lgkmcnt(0)
	v_pk_add_f32 v[6:7], v[6:7], v[4:5]
	v_pk_add_f32 v[8:9], v[8:9], v[2:3]
	ds_read_b128 v[2:5], v74 offset:50176
	s_waitcnt lgkmcnt(0)
	v_pk_add_f32 v[6:7], v[6:7], v[4:5]
	v_pk_add_f32 v[8:9], v[8:9], v[2:3]
	ds_read_b128 v[2:5], v74 offset:58624
	s_waitcnt lgkmcnt(0)
	v_pk_add_f32 v[6:7], v[6:7], v[4:5]
	v_pk_add_f32 v[8:9], v[8:9], v[2:3]
	ds_read_b128 v[2:5], v75 offset:50688
	s_waitcnt lgkmcnt(0)
	v_pk_add_f32 v[6:7], v[6:7], v[4:5]
	v_pk_add_f32 v[8:9], v[8:9], v[2:3]
	ds_read_b128 v[2:5], v75 offset:59136
	s_waitcnt lgkmcnt(0)
	v_pk_add_f32 v[8:9], v[8:9], v[2:3]
	v_or_b32_e32 v2, s2, v73
	v_ashrrev_i32_e32 v3, 31, v2
	v_lshl_add_u64 v[2:3], v[2:3], 2, s[14:15]
	v_pk_add_f32 v[6:7], v[6:7], v[4:5]
	global_load_dwordx4 v[2:5], v[2:3], off
	s_waitcnt vmcnt(0)
	v_mov_b32_e32 v10, v3
	v_mov_b32_e32 v11, v4
	v_mov_b32_e32 v3, v5
	v_mov_b32_e32 v5, v7
	v_pk_mov_b32 v[6:7], v[8:9], v[6:7] op_sel:[1,0]
	v_mov_b32_e32 v4, v8
	v_pk_add_f32 v[6:7], v[6:7], v[10:11]
	v_pk_add_f32 v[2:3], v[2:3], v[4:5]
	v_mul_f32_e32 v5, 0x3d372713, v6
	v_mul_f32_e32 v5, v6, v5
	v_fma_f32 v5, v6, v5, v6
	v_mul_f32_e32 v5, 0x3f4c422a, v5
	v_add_f32_e32 v5, v5, v5
	v_mul_f32_e32 v5, 0x3fb8aa3b, v5
	v_exp_f32_e32 v8, v5
	v_mul_f32_e32 v5, 0x3d372713, v7
	v_mul_f32_e32 v5, v7, v5
	v_fma_f32 v5, v7, v5, v7
	v_mul_f32_e32 v5, 0x3f4c422a, v5
	v_add_f32_e32 v5, v5, v5
	v_mul_f32_e32 v5, 0x3fb8aa3b, v5
	v_exp_f32_e32 v9, v5
	v_pk_mul_f32 v[6:7], v[6:7], 0.5 op_sel_hi:[1,0]
	v_mul_f32_e32 v4, 0x3d372713, v2
	v_mul_f32_e32 v4, v2, v4
	v_pk_add_f32 v[8:9], v[8:9], 1.0 op_sel_hi:[1,0]
	v_fma_f32 v4, v2, v4, v2
	v_div_scale_f32 v5, s[2:3], v9, v9, 2.0
	v_rcp_f32_e32 v10, v5
	v_mul_f32_e32 v4, 0x3f4c422a, v4
	v_add_f32_e32 v4, v4, v4
	v_mul_f32_e32 v4, 0x3fb8aa3b, v4
	v_fma_f32 v11, -v5, v10, 1.0
	v_fmac_f32_e32 v10, v11, v10
	v_div_scale_f32 v11, vcc, 2.0, v9, 2.0
	v_mul_f32_e32 v12, v11, v10
	v_fma_f32 v13, -v5, v12, v11
	v_fmac_f32_e32 v12, v13, v10
	v_fma_f32 v5, -v5, v12, v11
	v_div_fmas_f32 v5, v5, v10, v12
	v_div_fixup_f32 v9, v5, v9, 2.0
	v_div_scale_f32 v5, s[2:3], v8, v8, 2.0
	v_rcp_f32_e32 v10, v5
	v_exp_f32_e32 v4, v4
	v_fma_f32 v11, -v5, v10, 1.0
	v_fmac_f32_e32 v10, v11, v10
	v_div_scale_f32 v11, vcc, 2.0, v8, 2.0
	v_mul_f32_e32 v12, v11, v10
	v_fma_f32 v13, -v5, v12, v11
	v_fmac_f32_e32 v12, v13, v10
	v_fma_f32 v5, -v5, v12, v11
	v_div_fmas_f32 v5, v5, v10, v12
	v_div_fixup_f32 v8, v5, v8, 2.0
	v_pk_add_f32 v[8:9], v[8:9], 1.0 op_sel_hi:[1,0] neg_lo:[1,0] neg_hi:[1,0]
	s_nop 0
	v_pk_add_f32 v[8:9], v[8:9], 1.0 op_sel_hi:[1,0]
	s_nop 0
	v_pk_mul_f32 v[6:7], v[6:7], v[8:9]
	s_nop 0
	v_and_b32_sdwa v5, v7, v194 dst_sel:DWORD dst_unused:UNUSED_PAD src0_sel:WORD_1 src1_sel:DWORD
	v_and_b32_sdwa v8, v6, v194 dst_sel:DWORD dst_unused:UNUSED_PAD src0_sel:WORD_1 src1_sel:DWORD
	v_add3_u32 v7, v7, v5, s8
	v_add3_u32 v5, v6, v8, s8
	v_and_b32_e32 v6, 0xffff0000, v5
	v_mul_f32_e32 v5, 0x3d372713, v3
	v_mul_f32_e32 v5, v3, v5
	v_fma_f32 v5, v3, v5, v3
	v_mul_f32_e32 v5, 0x3f4c422a, v5
	v_add_f32_e32 v5, v5, v5
	v_mul_f32_e32 v5, 0x3fb8aa3b, v5
	v_exp_f32_e32 v5, v5
	v_pk_mul_f32 v[2:3], v[2:3], 0.5 op_sel_hi:[1,0]
	v_pk_add_f32 v[4:5], v[4:5], 1.0 op_sel_hi:[1,0]
	s_nop 0
	v_div_scale_f32 v8, s[2:3], v5, v5, 2.0
	v_rcp_f32_e32 v9, v8
	s_nop 0
	v_fma_f32 v10, -v8, v9, 1.0
	v_fmac_f32_e32 v9, v10, v9
	v_div_scale_f32 v10, vcc, 2.0, v5, 2.0
	v_mul_f32_e32 v11, v10, v9
	v_fma_f32 v12, -v8, v11, v10
	v_fmac_f32_e32 v11, v12, v9
	v_fma_f32 v8, -v8, v11, v10
	v_div_fmas_f32 v8, v8, v9, v11
	v_div_fixup_f32 v5, v8, v5, 2.0
	v_div_scale_f32 v8, s[2:3], v4, v4, 2.0
	v_rcp_f32_e32 v9, v8
	s_nop 0
	v_fma_f32 v10, -v8, v9, 1.0
	v_fmac_f32_e32 v9, v10, v9
	v_div_scale_f32 v10, vcc, 2.0, v4, 2.0
	v_mul_f32_e32 v11, v10, v9
	v_fma_f32 v12, -v8, v11, v10
	v_fmac_f32_e32 v11, v12, v9
	v_fma_f32 v8, -v8, v11, v10
	v_div_fmas_f32 v8, v8, v9, v11
	v_div_fixup_f32 v4, v8, v4, 2.0
	v_pk_add_f32 v[4:5], v[4:5], 1.0 op_sel_hi:[1,0] neg_lo:[1,0] neg_hi:[1,0]
	s_nop 0
	v_pk_add_f32 v[4:5], v[4:5], 1.0 op_sel_hi:[1,0]
	s_nop 0
	v_pk_mul_f32 v[2:3], v[2:3], v[4:5]
	s_nop 0
	v_and_b32_sdwa v4, v3, v194 dst_sel:DWORD dst_unused:UNUSED_PAD src0_sel:WORD_1 src1_sel:DWORD
	v_and_b32_sdwa v5, v2, v194 dst_sel:DWORD dst_unused:UNUSED_PAD src0_sel:WORD_1 src1_sel:DWORD
	v_add3_u32 v3, v3, v4, s8
	v_add3_u32 v2, v2, v5, s8
	v_and_b32_e32 v3, 0xffff0000, v3
	v_or_b32_sdwa v3, v3, v7 dst_sel:DWORD dst_unused:UNUSED_PAD src0_sel:DWORD src1_sel:WORD_1
	v_or_b32_sdwa v2, v2, v6 dst_sel:DWORD dst_unused:UNUSED_PAD src0_sel:WORD_1 src1_sel:DWORD
	ds_write_b64 v76, v[2:3]
	s_waitcnt lgkmcnt(0)
	s_barrier
	s_and_saveexec_b64 s[2:3], s[34:35]
	s_cbranch_execz .LBB0_553
	s_ashr_i32 s8, s16, 7
	s_ashr_i32 s9, s8, 31
	s_lshl_b64 s[8:9], s[8:9], 15
	v_lshl_add_u64 v[14:15], v[48:49], 0, s[8:9]
	global_load_dword v212, v[14:15], off
	global_load_dword v213, v[14:15], off offset:256
	global_load_dword v214, v[14:15], off offset:512
	global_load_dword v215, v[14:15], off offset:768
	global_load_dword v216, v[14:15], off offset:1024
	global_load_dword v217, v[14:15], off offset:1280
	global_load_dword v218, v[14:15], off offset:1536
	global_load_dword v219, v[14:15], off offset:1792
	s_movk_i32 s8, 0x2000
	v_add_co_u32_e32 v10, vcc, s8, v14
	s_nop 1
	v_addc_co_u32_e32 v11, vcc, 0, v15, vcc
	global_load_dword v220, v[10:11], off
	global_load_dword v221, v[10:11], off offset:256
	global_load_dword v222, v[10:11], off offset:512
	global_load_dword v223, v[10:11], off offset:768
	global_load_dword v224, v[10:11], off offset:1024
	global_load_dword v225, v[10:11], off offset:1280
	global_load_dword v226, v[10:11], off offset:1536
	global_load_dword v227, v[10:11], off offset:1792
	s_movk_i32 s8, 0x4000
	v_add_co_u32_e32 v10, vcc, s8, v14
	s_nop 1
	v_addc_co_u32_e32 v11, vcc, 0, v15, vcc
	global_load_dword v228, v[10:11], off
	global_load_dword v229, v[10:11], off offset:256
	global_load_dword v230, v[10:11], off offset:512
	global_load_dword v231, v[10:11], off offset:768
	global_load_dword v232, v[10:11], off offset:1024
	global_load_dword v233, v[10:11], off offset:1280
	global_load_dword v234, v[10:11], off offset:1536
	global_load_dword v235, v[10:11], off offset:1792
	s_movk_i32 s8, 0x6000
	v_add_co_u32_e32 v10, vcc, s8, v14
	s_nop 1
	v_addc_co_u32_e32 v11, vcc, 0, v15, vcc
	global_load_dword v236, v[10:11], off
	global_load_dword v237, v[10:11], off offset:256
	global_load_dword v238, v[10:11], off offset:512
	global_load_dword v239, v[10:11], off offset:768
	global_load_dword v240, v[10:11], off offset:1024
	global_load_dword v241, v[10:11], off offset:1280
	global_load_dword v242, v[10:11], off offset:1536
	global_load_dword v243, v[10:11], off offset:1792
	ds_read_b128 v[244:247], v77
	ds_read_b128 v[248:251], v77 offset:64
	ds_read_b128 v[138:141], v77 offset:128
	ds_read_b128 v[142:145], v77 offset:192
	s_waitcnt vmcnt(0) lgkmcnt(0)
	v_cvt_pk_bf16_f32 v6, v212, v213
	v_cvt_pk_bf16_f32 v7, v214, v215
	v_cvt_pk_bf16_f32 v8, v216, v217
	v_cvt_pk_bf16_f32 v9, v218, v219
	v_cvt_pk_bf16_f32 v10, v220, v221
	v_cvt_pk_bf16_f32 v11, v222, v223
	v_cvt_pk_bf16_f32 v12, v224, v225
	v_cvt_pk_bf16_f32 v13, v226, v227
	v_cvt_pk_bf16_f32 v16, v228, v229
	v_cvt_pk_bf16_f32 v17, v230, v231
	v_cvt_pk_bf16_f32 v18, v232, v233
	v_cvt_pk_bf16_f32 v19, v234, v235
	v_cvt_pk_bf16_f32 v20, v236, v237
	v_cvt_pk_bf16_f32 v21, v238, v239
	v_cvt_pk_bf16_f32 v22, v240, v241
	v_cvt_pk_bf16_f32 v23, v242, v243
	s_nop 1
	v_mfma_f32_16x16x32_bf16 v[2:5], v[244:247], v[6:9], 0
	v_mfma_f32_16x16x32_bf16 v[2:5], v[248:251], v[10:13], v[2:5]
	v_mfma_f32_16x16x32_bf16 v[2:5], v[138:141], v[16:19], v[2:5]
	v_mfma_f32_16x16x32_bf16 v[2:5], v[142:145], v[20:23], v[2:5]
	v_add_u32_e32 v6, 0x2000, v80
	s_nop 6
	ds_write2_b32 v6, v2, v3 offset1:65
	ds_write2_b32 v6, v4, v5 offset0:130 offset1:195
